# ATT_IN: dual K-loop, batched-cos/sin rope epilogue + V^T epilogue staged through LDS with whole-row stores
# speedup vs baseline: 1.0904x; 1.0230x over previous
; DI int obid() { int b = blockIdx.x; asm volatile("" : "+s"(b)); return b; }
; DI int ogrid() { int g = gridDim.x; asm volatile("" : "+s"(g)); return g; }
; #define STAGE(bufoff, GB) do { const char* g_ = (GB); \
;         _Pragma("unroll") for (int i_ = 0; i_ < 2; ++i_) __builtin_amdgcn_global_load_lds((const unsigned*)(g_ + voff[i_]), (LAS3 unsigned*)(L + (bufoff) + stoff + i_ * 8192), 16, 0, 0); } while (0)
; #define WAIT_V(n) asm volatile("s_waitcnt vmcnt(" #n ")" ::: "memory")
; #define BAR __builtin_amdgcn_s_barrier()
; #define VOFF_INIT() do { _Pragma("unroll") for (int i = 0; i < 2; ++i) { int R, C; stage_rc((wid * 64 + olane()) * 16 + i * 8192, R, C); voff[i] = (unsigned)(R * K + C) * 2u; } } while (0)
; template <int EPI>
; DI void gemm_phase(const bf16_t* __restrict__ A, const bf16_t* __restrict__ Bt, const int K, const int N, const Params& p, const int layer_j, char* lds) {
;     ...
;     if (obid() >= nwg) return;
;     int pm, pn;
;     TILE_COORDS(obid(), pm, pn);
;     const size_t kstep = 128, hstep = (size_t)HALF * K * 2, tstep = 2 * hstep;
;     const char* cA = (const char*)A + (size_t)pm * tstep; const char* cB = (const char*)Bt + (size_t)pn * tstep;
;     f32x4 acc[2][2][4][2];
; #pragma unroll
;     for (int a = 0; a < 2; ++a)
; #pragma unroll
;         for (int b = 0; b < 2; ++b)
; #pragma unroll
;             for (int m = 0; m < 4; ++m)
; #pragma unroll
;                 for (int n = 0; n < 2; ++n) acc[a][b][m][n] = (f32x4){0.f, 0.f, 0.f, 0.f};
;     bf16x8 At[4][2], B0[2][2], B1[2][2];
;     {
;         unsigned voff[2]; VOFF_INIT();
;         asm volatile("s_waitcnt vmcnt(0) lgkmcnt(0)" ::: "memory");
;         __syncthreads();
;         STAGE(SB(0, 0), cB); STAGE(SB(0, 1), cB + hstep); STAGE(SA(0, 0), cA); STAGE(SA(0, 1), cA + hstep);
;         if (wr == 1) BAR;
;         WAIT_V(2); BAR;
;         STAGE(SB(1, 0), cB + kstep); STAGE(SA(1, 0), cA + kstep); STAGE(SB(1, 1), cB + hstep + kstep);
;         WAIT_V(6); BAR;
;     }
;     for (int ui = 0;; ++ui) {
;         const int Lnext = (ui + 1) * ogrid() + obid();
;         const bool has_next = Lnext < nwg;
;         int pm2 = pm, pn2 = pn;
;         if (has_next) TILE_COORDS(Lnext, pm2, pn2);
;         const char* nA = (const char*)A + (size_t)pm2 * tstep; const char* nB = (const char*)Bt + (size_t)pn2 * tstep;
;         unsigned voff[2]; VOFF_INIT();
.LBB0_373:
	v_mbcnt_lo_u32_b32 v0, -1, 0
	v_mbcnt_hi_u32_b32 v0, -1, v0
	s_ashr_i32 s13, s12, 31
	v_add_u32_e32 v1, s71, v0
	v_ashrrev_i32_e32 v3, 6, v1
	v_lshlrev_b32_e32 v2, 4, v1
	v_lshrrev_b32_e32 v1, 31, v3
	v_add_u32_e32 v1, v3, v1
	v_and_b32_e32 v4, 32, v0
	v_ashrrev_i32_e32 v5, 1, v1
	v_and_b32_e32 v1, 0x3fffffe, v1
	v_lshlrev_b32_e32 v0, 9, v0
	v_sub_u32_e32 v1, v3, v1
	v_and_b32_e32 v6, 48, v2
	v_bitop3_b32 v2, v2, v4, 48 bitop3:0x6c
	v_and_b32_e32 v8, 0x7800, v0
	v_lshlrev_b32_e32 v1, 6, v1
	v_lshlrev_b32_e32 v7, 15, v5
	v_or_b32_e32 v0, v8, v2
	s_ashr_i32 s15, s14, 31
	v_add3_u32 v32, v1, v7, v0
	v_mbcnt_lo_u32_b32 v0, -1, 0
	v_mbcnt_hi_u32_b32 v0, -1, v0
	s_lshl_b64 s[18:19], s[12:13], 19
	v_add_lshl_u32 v1, v0, s71, 4
	s_lshl_b64 s[20:21], s[14:15], 19
	v_add_u32_e32 v2, 0x2000, v1
	v_ashrrev_i32_e32 v2, 10, v2
	s_add_u32 s13, s82, s18
	v_and_b32_e32 v7, 32, v0
	v_lshrrev_b32_e32 v9, 31, v2
	v_lshlrev_b32_e32 v0, 9, v0
	s_addc_u32 s15, s83, s19
	v_add_u32_e32 v9, v2, v9
	v_and_b32_e32 v11, 48, v1
	v_bitop3_b32 v1, v1, v7, 48 bitop3:0x6c
	v_and_b32_e32 v0, 0x7800, v0
	s_add_u32 s23, s34, s20
	v_ashrrev_i32_e32 v10, 1, v9
	v_and_b32_e32 v9, 0x3fffffe, v9
	v_or_b32_e32 v1, v0, v1
	s_addc_u32 s64, s35, s21
	v_sub_u32_e32 v9, v2, v9
	v_lshl_or_b32 v1, v10, 15, v1
	s_add_u32 s65, s25, s28
	s_movk_i32 s30, 0x7f80
	v_lshl_add_u32 v130, v9, 6, v1
	s_addc_u32 s66, s36, s29
	v_mul_lo_u32 v1, v10, s30
	v_bitop3_b32 v1, v11, v1, v7 bitop3:0xde
	v_lshlrev_b32_e32 v2, 6, v2
	s_add_u32 s28, s37, s26
	v_add3_u32 v0, v1, v0, v2
	v_mov_b32_e32 v1, v33
	s_addc_u32 s29, s38, s27
	v_lshl_add_u64 v[132:133], s[28:29], 0, v[0:1]
	v_mul_lo_u32 v0, v5, s30
	v_bitop3_b32 v0, v6, v0, v4 bitop3:0xde
	v_lshlrev_b32_e32 v1, 6, v3
	v_add3_u32 v0, v0, v8, v1
	v_mov_b32_e32 v1, v33
	v_lshl_add_u64 v[134:135], s[28:29], 0, v[0:1]
	s_add_u32 s67, s68, s26
	v_mov_b32_e32 v0, 0
	v_mov_b32_e32 v131, v33
	s_addc_u32 s86, s69, s27
	s_mov_b32 s87, -2
	s_mov_b64 s[26:27], 0
	v_mov_b32_e32 v1, v0
	v_mov_b32_e32 v2, v0
	v_mov_b32_e32 v3, v0
	v_mov_b32_e32 v8, v0
	v_mov_b32_e32 v9, v0
	v_mov_b32_e32 v10, v0
	v_mov_b32_e32 v11, v0
	v_mov_b32_e32 v4, v0
	v_mov_b32_e32 v5, v0
	v_mov_b32_e32 v6, v0
	v_mov_b32_e32 v7, v0
	v_mov_b32_e32 v16, v0
	v_mov_b32_e32 v17, v0
	v_mov_b32_e32 v18, v0
	v_mov_b32_e32 v19, v0
	v_mov_b32_e32 v28, v0
	v_mov_b32_e32 v29, v0
	v_mov_b32_e32 v30, v0
	v_mov_b32_e32 v31, v0
	v_mov_b32_e32 v70, v0
	v_mov_b32_e32 v71, v0
	v_mov_b32_e32 v72, v0
	v_mov_b32_e32 v73, v0
	v_mov_b32_e32 v42, v0
	v_mov_b32_e32 v43, v0
	v_mov_b32_e32 v44, v0
	v_mov_b32_e32 v45, v0
	v_mov_b32_e32 v86, v0
	v_mov_b32_e32 v87, v0
	v_mov_b32_e32 v88, v0
	v_mov_b32_e32 v89, v0
	v_mov_b32_e32 v58, v0
	v_mov_b32_e32 v59, v0
	v_mov_b32_e32 v60, v0
	v_mov_b32_e32 v61, v0
	v_mov_b32_e32 v90, v0
	v_mov_b32_e32 v91, v0
	v_mov_b32_e32 v92, v0
	v_mov_b32_e32 v93, v0
	v_mov_b32_e32 v66, v0
	v_mov_b32_e32 v67, v0
	v_mov_b32_e32 v68, v0
	v_mov_b32_e32 v69, v0
	v_mov_b32_e32 v98, v0
	v_mov_b32_e32 v99, v0
	v_mov_b32_e32 v100, v0
	v_mov_b32_e32 v101, v0
	v_mov_b32_e32 v12, v0
	v_mov_b32_e32 v13, v0
	v_mov_b32_e32 v14, v0
	v_mov_b32_e32 v15, v0
	v_mov_b32_e32 v38, v0
	v_mov_b32_e32 v39, v0
	v_mov_b32_e32 v40, v0
	v_mov_b32_e32 v41, v0
	v_mov_b32_e32 v20, v0
	v_mov_b32_e32 v21, v0
	v_mov_b32_e32 v22, v0
	v_mov_b32_e32 v23, v0
	v_mov_b32_e32 v54, v0
	v_mov_b32_e32 v55, v0
	v_mov_b32_e32 v56, v0
	v_mov_b32_e32 v57, v0
	v_mov_b32_e32 v24, v0
	v_mov_b32_e32 v25, v0
	v_mov_b32_e32 v26, v0
	v_mov_b32_e32 v27, v0
	v_mov_b32_e32 v62, v0
	v_mov_b32_e32 v63, v0
	v_mov_b32_e32 v64, v0
	v_mov_b32_e32 v65, v0
	v_mov_b32_e32 v34, v0
	v_mov_b32_e32 v35, v0
	v_mov_b32_e32 v36, v0
	v_mov_b32_e32 v37, v0
	v_mov_b32_e32 v74, v0
	v_mov_b32_e32 v75, v0
	v_mov_b32_e32 v76, v0
	v_mov_b32_e32 v77, v0
	v_mov_b32_e32 v94, v0
	v_mov_b32_e32 v95, v0
	v_mov_b32_e32 v96, v0
	v_mov_b32_e32 v97, v0
	v_mov_b32_e32 v114, v0
	v_mov_b32_e32 v115, v0
	v_mov_b32_e32 v116, v0
	v_mov_b32_e32 v117, v0
	v_mov_b32_e32 v102, v0
	v_mov_b32_e32 v103, v0
	v_mov_b32_e32 v104, v0
	v_mov_b32_e32 v105, v0
	v_mov_b32_e32 v118, v0
	v_mov_b32_e32 v119, v0
	v_mov_b32_e32 v120, v0
	v_mov_b32_e32 v121, v0
	v_mov_b32_e32 v106, v0
	v_mov_b32_e32 v107, v0
	v_mov_b32_e32 v108, v0
	v_mov_b32_e32 v109, v0
	v_mov_b32_e32 v122, v0
	v_mov_b32_e32 v123, v0
	v_mov_b32_e32 v124, v0
	v_mov_b32_e32 v125, v0
	v_mov_b32_e32 v110, v0
	v_mov_b32_e32 v111, v0
	v_mov_b32_e32 v112, v0
	v_mov_b32_e32 v113, v0
	v_mov_b32_e32 v126, v0
	v_mov_b32_e32 v127, v0
	v_mov_b32_e32 v128, v0
	v_mov_b32_e32 v129, v0
	v_mov_b32_e32 v78, v0
	v_mov_b32_e32 v79, v0
	v_mov_b32_e32 v80, v0
	v_mov_b32_e32 v81, v0
	v_mov_b32_e32 v46, v0
	v_mov_b32_e32 v47, v0
	v_mov_b32_e32 v48, v0
	v_mov_b32_e32 v49, v0
	v_mov_b32_e32 v82, v0
	v_mov_b32_e32 v83, v0
	v_mov_b32_e32 v84, v0
	v_mov_b32_e32 v85, v0
	v_mov_b32_e32 v50, v0
	v_mov_b32_e32 v51, v0
	v_mov_b32_e32 v52, v0
	v_mov_b32_e32 v53, v0
	s_lshr_b32 s28, s24, 1
	s_cmp_eq_u32 s28, 2
	s_cbranch_scc1 .Latt_kloop_ns
	s_cmp_eq_u32 s28, 5
	s_cbranch_scc1 .Latt_kloop_ns
; #define STAGE(bufoff, GB) do { const char* g_ = (GB); \
;         _Pragma("unroll") for (int i_ = 0; i_ < 2; ++i_) __builtin_amdgcn_global_load_lds((const unsigned*)(g_ + voff[i_]), (LAS3 unsigned*)(L + (bufoff) + stoff + i_ * 8192), 16, 0, 0); } while (0)
; #define LDA(dst, b, h) do { _Pragma("unroll") for (int m = 0; m < 4; ++m) _Pragma("unroll") for (int k = 0; k < 2; ++k) dst[m][k] = *(const LAS3 bf16x8*)(L + SA(b, h) + aoff + m * 2048 + k * 1024); } while (0)
; #define LDB(dst, b, h) do { _Pragma("unroll") for (int n = 0; n < 2; ++n) _Pragma("unroll") for (int k = 0; k < 2; ++k) dst[n][k] = *(const LAS3 bf16x8*)(L + SB(b, h) + boff + n * 2048 + k * 1024); } while (0)
; #define WAIT_V(n) asm volatile("s_waitcnt vmcnt(" #n ")" ::: "memory")
; #define WAIT_L(n) asm volatile("s_waitcnt lgkmcnt(" #n ")" ::: "memory")
; #define BAR __builtin_amdgcn_s_barrier()
; #define SCHED __builtin_amdgcn_sched_barrier(0)
; template <int EPI>
; DI void gemm_phase(const bf16_t* __restrict__ A, const bf16_t* __restrict__ Bt, const int K, const int N, const Params& p, const int layer_j, char* lds) {
;     ...
;         for (int t = 0; t < nt; t += 2) {
;             const bool last = (t == nt - 2);
;             const char* a1 = cA + (size_t)(t + 1) * kstep;
;             const char* a2 = last ? nA : cA + (size_t)(t + 2) * kstep; const char* b2 = last ? nB : cB + (size_t)(t + 2) * kstep;
;             const char* a3 = a2 + kstep; const char* b3 = b2 + kstep;
;             LDB(B0, 0, 0); LDB(B1, 0, 1); SCHED; LDA(At, 0, 0); STAGE(SA(1, 1), a1 + hstep);
;             WAIT_V(8); WAIT_L(0); BAR; MMA(0, 0, At, B0); MMA(0, 1, At, B1); BAR; SCHED;
;             LDA(At, 0, 1); STAGE(SB(0, 0), b2); STAGE(SB(0, 1), b2 + hstep); STAGE(SA(0, 0), a2);
;             WAIT_V(8); WAIT_L(0); BAR; MMA(1, 0, At, B0); MMA(1, 1, At, B1); BAR; SCHED;
.LBB0_374:
	v_add_u32_e32 v136, 0x10000, v140
	ds_read_b128 v[154:157], v136
	ds_read_b128 v[158:161], v136 offset:1024
	ds_read_b128 v[162:165], v136 offset:2048
	ds_read_b128 v[166:169], v136 offset:3072
	v_add_u32_e32 v136, 0x14000, v140
	s_add_u32 s28, s67, s26
	ds_read_b128 v[170:173], v136
	ds_read_b128 v[174:177], v136 offset:1024
	ds_read_b128 v[178:181], v136 offset:2048
	ds_read_b128 v[182:185], v136 offset:3072
	s_addc_u32 s29, s86, s27
	s_add_u32 s28, s28, 0x6681100
	s_addc_u32 s29, s29, 0
	s_add_u32 s88, s65, s26
	s_addc_u32 vcc_lo, s66, s27
	s_cmpk_eq_i32 s26, 0x700
	s_cselect_b32 s31, s15, s29
	s_cselect_b32 s30, s13, s28
	s_cselect_b32 s29, s64, vcc_lo
	s_cselect_b32 s28, s23, s88
	v_add_u32_e32 v190, 0xc000, v138
	v_lshl_add_u64 v[136:137], v[134:135], 0, s[26:27]
	v_readfirstlane_b32 s88, v190
	v_add_u32_e32 v190, 0xe000, v138
	s_mov_b32 m0, s88
	v_readfirstlane_b32 s88, v190
	ds_read_b128 v[186:189], v139
	ds_read_b128 v[204:207], v139 offset:1024
	ds_read_b128 v[208:211], v139 offset:2048
	ds_read_b128 v[212:215], v139 offset:3072
	ds_read_b128 v[216:219], v139 offset:4096
	ds_read_b128 v[220:223], v139 offset:5120
	ds_read_b128 v[224:227], v139 offset:6144
	ds_read_b128 v[228:231], v139 offset:7168
	global_load_lds_dwordx4 v[136:137], off
	v_lshl_add_u64 v[136:137], v[132:133], 0, s[26:27]
	s_mov_b32 m0, s88
	s_nop 0
	global_load_lds_dwordx4 v[136:137], off
	s_waitcnt vmcnt(8)
	s_waitcnt lgkmcnt(0)
	s_barrier
	s_setprio 1
	s_waitcnt lgkmcnt(0)
	v_mfma_f32_16x16x32_bf16 v[126:129], v[154:157], v[186:189], v[126:129]
	v_mfma_f32_16x16x32_bf16 v[110:113], v[162:165], v[186:189], v[110:113]
	v_mfma_f32_16x16x32_bf16 v[122:125], v[154:157], v[208:211], v[122:125]
	v_mfma_f32_16x16x32_bf16 v[106:109], v[162:165], v[208:211], v[106:109]
	v_mfma_f32_16x16x32_bf16 v[118:121], v[154:157], v[216:219], v[118:121]
	v_mfma_f32_16x16x32_bf16 v[102:105], v[162:165], v[216:219], v[102:105]
	v_mfma_f32_16x16x32_bf16 v[114:117], v[154:157], v[224:227], v[114:117]
	v_mfma_f32_16x16x32_bf16 v[94:97], v[162:165], v[224:227], v[94:97]
	v_mfma_f32_16x16x32_bf16 v[126:129], v[158:161], v[204:207], v[126:129]
	v_mfma_f32_16x16x32_bf16 v[110:113], v[166:169], v[204:207], v[110:113]
	v_mfma_f32_16x16x32_bf16 v[122:125], v[158:161], v[212:215], v[122:125]
	v_mfma_f32_16x16x32_bf16 v[106:109], v[166:169], v[212:215], v[106:109]
	v_mfma_f32_16x16x32_bf16 v[118:121], v[158:161], v[220:223], v[118:121]
	v_mfma_f32_16x16x32_bf16 v[102:105], v[166:169], v[220:223], v[102:105]
	v_mfma_f32_16x16x32_bf16 v[114:117], v[158:161], v[228:231], v[114:117]
	v_mfma_f32_16x16x32_bf16 v[94:97], v[166:169], v[228:231], v[94:97]
	s_setprio 0
	s_setprio 1
	v_mfma_f32_16x16x32_bf16 v[74:77], v[170:173], v[186:189], v[74:77]
	v_mfma_f32_16x16x32_bf16 v[34:37], v[178:181], v[186:189], v[34:37]
	v_mfma_f32_16x16x32_bf16 v[62:65], v[170:173], v[208:211], v[62:65]
	v_mfma_f32_16x16x32_bf16 v[24:27], v[178:181], v[208:211], v[24:27]
	v_mfma_f32_16x16x32_bf16 v[54:57], v[170:173], v[216:219], v[54:57]
	v_mfma_f32_16x16x32_bf16 v[20:23], v[178:181], v[216:219], v[20:23]
	v_mfma_f32_16x16x32_bf16 v[38:41], v[170:173], v[224:227], v[38:41]
	v_mfma_f32_16x16x32_bf16 v[12:15], v[178:181], v[224:227], v[12:15]
	v_mfma_f32_16x16x32_bf16 v[74:77], v[174:177], v[204:207], v[74:77]
	v_mfma_f32_16x16x32_bf16 v[34:37], v[182:185], v[204:207], v[34:37]
	v_mfma_f32_16x16x32_bf16 v[62:65], v[174:177], v[212:215], v[62:65]
	v_mfma_f32_16x16x32_bf16 v[24:27], v[182:185], v[212:215], v[24:27]
	v_mfma_f32_16x16x32_bf16 v[54:57], v[174:177], v[220:223], v[54:57]
	v_mfma_f32_16x16x32_bf16 v[20:23], v[182:185], v[220:223], v[20:23]
	v_mfma_f32_16x16x32_bf16 v[38:41], v[174:177], v[228:231], v[38:41]
	v_mfma_f32_16x16x32_bf16 v[12:15], v[182:185], v[228:231], v[12:15]
	s_setprio 0
	s_barrier
	v_readfirstlane_b32 s88, v141
	v_lshl_add_u64 v[136:137], s[28:29], 0, v[32:33]
	s_mov_b32 m0, s88
	v_readfirstlane_b32 s88, v142
	s_add_u32 vcc_lo, s28, 0x40000
	ds_read_b128 v[186:189], v139 offset:16384
	ds_read_b128 v[204:207], v139 offset:17408
	ds_read_b128 v[208:211], v139 offset:18432
	ds_read_b128 v[212:215], v139 offset:19456
	ds_read_b128 v[216:219], v139 offset:20480
	ds_read_b128 v[220:223], v139 offset:21504
	ds_read_b128 v[224:227], v139 offset:22528
	ds_read_b128 v[228:231], v139 offset:23552
	global_load_lds_dwordx4 v[136:137], off
	v_lshl_add_u64 v[190:191], s[28:29], 0, v[130:131]
	s_mov_b32 m0, s88
	s_addc_u32 vcc_hi, s29, 0
	v_readfirstlane_b32 s88, v143
	global_load_lds_dwordx4 v[190:191], off
	v_lshl_add_u64 v[194:195], vcc, 0, v[32:33]
	s_mov_b32 m0, s88
	v_readfirstlane_b32 s88, v144
	global_load_lds_dwordx4 v[194:195], off
	v_lshl_add_u64 v[194:195], vcc, 0, v[130:131]
	s_mov_b32 m0, s88
	v_readfirstlane_b32 s88, v138
	global_load_lds_dwordx4 v[194:195], off
	v_lshl_add_u64 v[194:195], s[30:31], 0, v[32:33]
	s_mov_b32 m0, s88
	v_readfirstlane_b32 s88, v145
	global_load_lds_dwordx4 v[194:195], off
	v_lshl_add_u64 v[232:233], s[30:31], 0, v[130:131]
	s_mov_b32 m0, s88
	s_nop 0
	global_load_lds_dwordx4 v[232:233], off
	s_waitcnt vmcnt(8)
	s_waitcnt lgkmcnt(0)
	s_barrier
; #define STAGE(bufoff, GB) do { const char* g_ = (GB); \
;         _Pragma("unroll") for (int i_ = 0; i_ < 2; ++i_) __builtin_amdgcn_global_load_lds((const unsigned*)(g_ + voff[i_]), (LAS3 unsigned*)(L + (bufoff) + stoff + i_ * 8192), 16, 0, 0); } while (0)
; #define LDA(dst, b, h) do { _Pragma("unroll") for (int m = 0; m < 4; ++m) _Pragma("unroll") for (int k = 0; k < 2; ++k) dst[m][k] = *(const LAS3 bf16x8*)(L + SA(b, h) + aoff + m * 2048 + k * 1024); } while (0)
; #define LDB(dst, b, h) do { _Pragma("unroll") for (int n = 0; n < 2; ++n) _Pragma("unroll") for (int k = 0; k < 2; ++k) dst[n][k] = *(const LAS3 bf16x8*)(L + SB(b, h) + boff + n * 2048 + k * 1024); } while (0)
; #define WAIT_V(n) asm volatile("s_waitcnt vmcnt(" #n ")" ::: "memory")
; #define WAIT_L(n) asm volatile("s_waitcnt lgkmcnt(" #n ")" ::: "memory")
; #define BAR __builtin_amdgcn_s_barrier()
; #define SCHED __builtin_amdgcn_sched_barrier(0)
; template <int EPI>
; DI void gemm_phase(const bf16_t* __restrict__ A, const bf16_t* __restrict__ Bt, const int K, const int N, const Params& p, const int layer_j, char* lds) {
;     ...
;             LDA(At, 0, 1); STAGE(SB(0, 0), b2); STAGE(SB(0, 1), b2 + hstep); STAGE(SA(0, 0), a2);
;             WAIT_V(8); WAIT_L(0); BAR; MMA(1, 0, At, B0); MMA(1, 1, At, B1); BAR; SCHED;
;             LDB(B0, 1, 0); LDB(B1, 1, 1); SCHED; LDA(At, 1, 0); STAGE(SA(0, 1), a2 + hstep);
;             WAIT_V(8); WAIT_L(0); BAR; MMA(0, 0, At, B0); MMA(0, 1, At, B1); BAR; SCHED;
	s_setprio 1
	s_waitcnt lgkmcnt(0)
	v_mfma_f32_16x16x32_bf16 v[98:101], v[154:157], v[186:189], v[98:101]
	v_mfma_f32_16x16x32_bf16 v[66:69], v[162:165], v[186:189], v[66:69]
	v_mfma_f32_16x16x32_bf16 v[90:93], v[154:157], v[208:211], v[90:93]
	v_mfma_f32_16x16x32_bf16 v[58:61], v[162:165], v[208:211], v[58:61]
	v_mfma_f32_16x16x32_bf16 v[86:89], v[154:157], v[216:219], v[86:89]
	v_mfma_f32_16x16x32_bf16 v[42:45], v[162:165], v[216:219], v[42:45]
	v_mfma_f32_16x16x32_bf16 v[70:73], v[154:157], v[224:227], v[70:73]
	v_mfma_f32_16x16x32_bf16 v[28:31], v[162:165], v[224:227], v[28:31]
	v_mfma_f32_16x16x32_bf16 v[98:101], v[158:161], v[204:207], v[98:101]
	v_mfma_f32_16x16x32_bf16 v[66:69], v[166:169], v[204:207], v[66:69]
	v_mfma_f32_16x16x32_bf16 v[90:93], v[158:161], v[212:215], v[90:93]
	v_mfma_f32_16x16x32_bf16 v[58:61], v[166:169], v[212:215], v[58:61]
	v_mfma_f32_16x16x32_bf16 v[86:89], v[158:161], v[220:223], v[86:89]
	v_mfma_f32_16x16x32_bf16 v[42:45], v[166:169], v[220:223], v[42:45]
	v_mfma_f32_16x16x32_bf16 v[70:73], v[158:161], v[228:231], v[70:73]
	v_mfma_f32_16x16x32_bf16 v[28:31], v[166:169], v[228:231], v[28:31]
	s_setprio 0
	s_setprio 1
	v_mfma_f32_16x16x32_bf16 v[16:19], v[170:173], v[186:189], v[16:19]
	v_mfma_f32_16x16x32_bf16 v[4:7], v[178:181], v[186:189], v[4:7]
	v_mfma_f32_16x16x32_bf16 v[8:11], v[170:173], v[208:211], v[8:11]
	v_mfma_f32_16x16x32_bf16 v[0:3], v[178:181], v[208:211], v[0:3]
	v_mfma_f32_16x16x32_bf16 v[78:81], v[170:173], v[216:219], v[78:81]
	v_mfma_f32_16x16x32_bf16 v[46:49], v[178:181], v[216:219], v[46:49]
	v_mfma_f32_16x16x32_bf16 v[82:85], v[170:173], v[224:227], v[82:85]
	v_mfma_f32_16x16x32_bf16 v[50:53], v[178:181], v[224:227], v[50:53]
	v_mfma_f32_16x16x32_bf16 v[16:19], v[174:177], v[204:207], v[16:19]
	v_mfma_f32_16x16x32_bf16 v[4:7], v[182:185], v[204:207], v[4:7]
	v_mfma_f32_16x16x32_bf16 v[8:11], v[174:177], v[212:215], v[8:11]
	v_mfma_f32_16x16x32_bf16 v[0:3], v[182:185], v[212:215], v[0:3]
	v_mfma_f32_16x16x32_bf16 v[78:81], v[174:177], v[220:223], v[78:81]
	v_mfma_f32_16x16x32_bf16 v[46:49], v[182:185], v[220:223], v[46:49]
	v_mfma_f32_16x16x32_bf16 v[82:85], v[174:177], v[228:231], v[82:85]
	v_mfma_f32_16x16x32_bf16 v[50:53], v[182:185], v[228:231], v[50:53]
	s_setprio 0
	s_barrier
	v_add_u32_e32 v166, 0x18000, v140
	v_add_u32_e32 v182, 0x1c000, v140
	ds_read_b128 v[154:157], v166
	ds_read_b128 v[158:161], v166 offset:1024
	ds_read_b128 v[162:165], v166 offset:2048
	ds_read_b128 v[166:169], v166 offset:3072
	ds_read_b128 v[170:173], v182
	ds_read_b128 v[174:177], v182 offset:1024
	ds_read_b128 v[178:181], v182 offset:2048
	ds_read_b128 v[182:185], v182 offset:3072
	s_add_u32 s30, s30, 0x40000
	s_addc_u32 s31, s31, 0
	v_readfirstlane_b32 s88, v146
	v_lshl_add_u64 v[234:235], s[30:31], 0, v[32:33]
	s_mov_b32 m0, s88
	ds_read_b128 v[186:189], v139 offset:32768
	ds_read_b128 v[204:207], v139 offset:33792
	ds_read_b128 v[208:211], v139 offset:34816
	ds_read_b128 v[212:215], v139 offset:35840
	ds_read_b128 v[216:219], v139 offset:36864
	ds_read_b128 v[220:223], v139 offset:37888
	ds_read_b128 v[224:227], v139 offset:38912
	ds_read_b128 v[228:231], v139 offset:39936
	global_load_lds_dwordx4 v[234:235], off
	v_lshl_add_u64 v[234:235], s[30:31], 0, v[130:131]
	v_readfirstlane_b32 s30, v147
	s_mov_b32 m0, s30
	s_nop 0
	global_load_lds_dwordx4 v[234:235], off
	s_waitcnt vmcnt(8)
	s_waitcnt lgkmcnt(0)
	s_barrier
	s_setprio 1
	s_waitcnt lgkmcnt(0)
	v_mfma_f32_16x16x32_bf16 v[126:129], v[154:157], v[186:189], v[126:129]
	v_mfma_f32_16x16x32_bf16 v[110:113], v[162:165], v[186:189], v[110:113]
	v_mfma_f32_16x16x32_bf16 v[122:125], v[154:157], v[208:211], v[122:125]
	v_mfma_f32_16x16x32_bf16 v[106:109], v[162:165], v[208:211], v[106:109]
	v_mfma_f32_16x16x32_bf16 v[118:121], v[154:157], v[216:219], v[118:121]
	v_mfma_f32_16x16x32_bf16 v[102:105], v[162:165], v[216:219], v[102:105]
	v_mfma_f32_16x16x32_bf16 v[114:117], v[154:157], v[224:227], v[114:117]
	v_mfma_f32_16x16x32_bf16 v[94:97], v[162:165], v[224:227], v[94:97]
	v_mfma_f32_16x16x32_bf16 v[126:129], v[158:161], v[204:207], v[126:129]
	v_mfma_f32_16x16x32_bf16 v[110:113], v[166:169], v[204:207], v[110:113]
	v_mfma_f32_16x16x32_bf16 v[122:125], v[158:161], v[212:215], v[122:125]
	v_mfma_f32_16x16x32_bf16 v[106:109], v[166:169], v[212:215], v[106:109]
	v_mfma_f32_16x16x32_bf16 v[118:121], v[158:161], v[220:223], v[118:121]
	v_mfma_f32_16x16x32_bf16 v[102:105], v[166:169], v[220:223], v[102:105]
	v_mfma_f32_16x16x32_bf16 v[114:117], v[158:161], v[228:231], v[114:117]
	v_mfma_f32_16x16x32_bf16 v[94:97], v[166:169], v[228:231], v[94:97]
	s_setprio 0
	s_setprio 1
	v_mfma_f32_16x16x32_bf16 v[74:77], v[170:173], v[186:189], v[74:77]
	v_mfma_f32_16x16x32_bf16 v[34:37], v[178:181], v[186:189], v[34:37]
	v_mfma_f32_16x16x32_bf16 v[62:65], v[170:173], v[208:211], v[62:65]
	v_mfma_f32_16x16x32_bf16 v[24:27], v[178:181], v[208:211], v[24:27]
	v_mfma_f32_16x16x32_bf16 v[54:57], v[170:173], v[216:219], v[54:57]
	v_mfma_f32_16x16x32_bf16 v[20:23], v[178:181], v[216:219], v[20:23]
	v_mfma_f32_16x16x32_bf16 v[38:41], v[170:173], v[224:227], v[38:41]
	v_mfma_f32_16x16x32_bf16 v[12:15], v[178:181], v[224:227], v[12:15]
	v_mfma_f32_16x16x32_bf16 v[74:77], v[174:177], v[204:207], v[74:77]
	v_mfma_f32_16x16x32_bf16 v[34:37], v[182:185], v[204:207], v[34:37]
	v_mfma_f32_16x16x32_bf16 v[62:65], v[174:177], v[212:215], v[62:65]
	v_mfma_f32_16x16x32_bf16 v[24:27], v[182:185], v[212:215], v[24:27]
	v_mfma_f32_16x16x32_bf16 v[54:57], v[174:177], v[220:223], v[54:57]
	v_mfma_f32_16x16x32_bf16 v[20:23], v[182:185], v[220:223], v[20:23]
	v_mfma_f32_16x16x32_bf16 v[38:41], v[174:177], v[228:231], v[38:41]
	v_mfma_f32_16x16x32_bf16 v[12:15], v[182:185], v[228:231], v[12:15]
	s_setprio 0
	s_barrier
; #define STAGE(bufoff, GB) do { const char* g_ = (GB); \
;         _Pragma("unroll") for (int i_ = 0; i_ < 2; ++i_) __builtin_amdgcn_global_load_lds((const unsigned*)(g_ + voff[i_]), (LAS3 unsigned*)(L + (bufoff) + stoff + i_ * 8192), 16, 0, 0); } while (0)
; #define LDA(dst, b, h) do { _Pragma("unroll") for (int m = 0; m < 4; ++m) _Pragma("unroll") for (int k = 0; k < 2; ++k) dst[m][k] = *(const LAS3 bf16x8*)(L + SA(b, h) + aoff + m * 2048 + k * 1024); } while (0)
; #define WAIT_V(n) asm volatile("s_waitcnt vmcnt(" #n ")" ::: "memory")
; #define WAIT_L(n) asm volatile("s_waitcnt lgkmcnt(" #n ")" ::: "memory")
; #define BAR __builtin_amdgcn_s_barrier()
; #define SCHED __builtin_amdgcn_sched_barrier(0)
; template <int EPI>
; DI void gemm_phase(const bf16_t* __restrict__ A, const bf16_t* __restrict__ Bt, const int K, const int N, const Params& p, const int layer_j, char* lds) {
;     ...
;             LDA(At, 1, 1); STAGE(SB(1, 0), b3); STAGE(SB(1, 1), b3 + hstep); STAGE(SA(1, 0), a3);
;             WAIT_V(8); WAIT_L(0); BAR; MMA(1, 0, At, B0); MMA(1, 1, At, B1); BAR; SCHED;
;         }
	v_readfirstlane_b32 s30, v148
	v_lshl_add_u64 v[136:137], v[136:137], 0, s[94:95]
	s_mov_b32 m0, s30
	v_readfirstlane_b32 s30, v149
	s_add_u32 s28, s28, 0x40080
	ds_read_b128 v[186:189], v139 offset:49152
	ds_read_b128 v[204:207], v139 offset:50176
	ds_read_b128 v[208:211], v139 offset:51200
	ds_read_b128 v[212:215], v139 offset:52224
	ds_read_b128 v[216:219], v139 offset:53248
	ds_read_b128 v[220:223], v139 offset:54272
	ds_read_b128 v[224:227], v139 offset:55296
	ds_read_b128 v[228:231], v139 offset:56320
	global_load_lds_dwordx4 v[136:137], off
	v_lshl_add_u64 v[136:137], v[190:191], 0, s[94:95]
	s_mov_b32 m0, s30
	s_addc_u32 s29, s29, 0
	v_readfirstlane_b32 s30, v152
	global_load_lds_dwordx4 v[136:137], off
	v_lshl_add_u64 v[136:137], s[28:29], 0, v[32:33]
	s_mov_b32 m0, s30
	s_nop 0
	global_load_lds_dwordx4 v[136:137], off
	v_lshl_add_u64 v[136:137], s[28:29], 0, v[130:131]
	v_readfirstlane_b32 s28, v153
	s_mov_b32 m0, s28
	v_readfirstlane_b32 s28, v150
	global_load_lds_dwordx4 v[136:137], off
	v_lshl_add_u64 v[136:137], v[194:195], 0, s[94:95]
	s_mov_b32 m0, s28
	v_readfirstlane_b32 s28, v151
	global_load_lds_dwordx4 v[136:137], off
	v_lshl_add_u64 v[136:137], v[232:233], 0, s[94:95]
	s_mov_b32 m0, s28
	s_nop 0
	global_load_lds_dwordx4 v[136:137], off
	s_waitcnt vmcnt(8)
	s_waitcnt lgkmcnt(0)
	s_barrier
	s_setprio 1
	s_waitcnt lgkmcnt(0)
	v_mfma_f32_16x16x32_bf16 v[98:101], v[154:157], v[186:189], v[98:101]
	v_mfma_f32_16x16x32_bf16 v[66:69], v[162:165], v[186:189], v[66:69]
	v_mfma_f32_16x16x32_bf16 v[90:93], v[154:157], v[208:211], v[90:93]
	v_mfma_f32_16x16x32_bf16 v[58:61], v[162:165], v[208:211], v[58:61]
	v_mfma_f32_16x16x32_bf16 v[86:89], v[154:157], v[216:219], v[86:89]
	v_mfma_f32_16x16x32_bf16 v[42:45], v[162:165], v[216:219], v[42:45]
	v_mfma_f32_16x16x32_bf16 v[70:73], v[154:157], v[224:227], v[70:73]
	v_mfma_f32_16x16x32_bf16 v[28:31], v[162:165], v[224:227], v[28:31]
	v_mfma_f32_16x16x32_bf16 v[98:101], v[158:161], v[204:207], v[98:101]
	v_mfma_f32_16x16x32_bf16 v[66:69], v[166:169], v[204:207], v[66:69]
	v_mfma_f32_16x16x32_bf16 v[90:93], v[158:161], v[212:215], v[90:93]
	v_mfma_f32_16x16x32_bf16 v[58:61], v[166:169], v[212:215], v[58:61]
	v_mfma_f32_16x16x32_bf16 v[86:89], v[158:161], v[220:223], v[86:89]
	v_mfma_f32_16x16x32_bf16 v[42:45], v[166:169], v[220:223], v[42:45]
	v_mfma_f32_16x16x32_bf16 v[70:73], v[158:161], v[228:231], v[70:73]
	v_mfma_f32_16x16x32_bf16 v[28:31], v[166:169], v[228:231], v[28:31]
	s_setprio 0
	s_setprio 1
	v_mfma_f32_16x16x32_bf16 v[16:19], v[170:173], v[186:189], v[16:19]
	v_mfma_f32_16x16x32_bf16 v[4:7], v[178:181], v[186:189], v[4:7]
	v_mfma_f32_16x16x32_bf16 v[8:11], v[170:173], v[208:211], v[8:11]
	v_mfma_f32_16x16x32_bf16 v[0:3], v[178:181], v[208:211], v[0:3]
	v_mfma_f32_16x16x32_bf16 v[78:81], v[170:173], v[216:219], v[78:81]
	v_mfma_f32_16x16x32_bf16 v[46:49], v[178:181], v[216:219], v[46:49]
	v_mfma_f32_16x16x32_bf16 v[82:85], v[170:173], v[224:227], v[82:85]
	v_mfma_f32_16x16x32_bf16 v[50:53], v[178:181], v[224:227], v[50:53]
	v_mfma_f32_16x16x32_bf16 v[16:19], v[174:177], v[204:207], v[16:19]
	v_mfma_f32_16x16x32_bf16 v[4:7], v[182:185], v[204:207], v[4:7]
	v_mfma_f32_16x16x32_bf16 v[8:11], v[174:177], v[212:215], v[8:11]
	v_mfma_f32_16x16x32_bf16 v[0:3], v[182:185], v[212:215], v[0:3]
	v_mfma_f32_16x16x32_bf16 v[78:81], v[174:177], v[220:223], v[78:81]
	v_mfma_f32_16x16x32_bf16 v[46:49], v[182:185], v[220:223], v[46:49]
	v_mfma_f32_16x16x32_bf16 v[82:85], v[174:177], v[228:231], v[82:85]
	v_mfma_f32_16x16x32_bf16 v[50:53], v[182:185], v[228:231], v[50:53]
	s_setprio 0
	s_barrier
	s_add_i32 s87, s87, 2
	s_add_u32 s26, s26, 0x100
	s_addc_u32 s27, s27, 0
	s_cmp_gt_u32 s87, 13
	s_cbranch_scc0 .LBB0_374
	s_branch .Latt_kloop_done

; DI int olane() { int l; asm volatile("v_mbcnt_lo_u32_b32 %0, -1, 0\n\tv_mbcnt_hi_u32_b32 %0, -1, %0" : "=v"(l)); return l; }
; #define BAR __builtin_amdgcn_s_barrier()
; template <int EPI>
; DI void gemm_phase(const bf16_t* __restrict__ A, const bf16_t* __restrict__ Bt, const int K, const int N, const Params& p, const int layer_j, char* lds) {
;     ...
;         if (wr == 0) BAR;
;         const int le = olane(), fr = le & 15, fq = le >> 4;
;     ...
;             const int region = col0 >> 9;
;             if (region == 2 || region == 5) {
.Latt_kloop_done:
	v_readlane_b32 s26, v254, 12
	v_readlane_b32 s27, v254, 13
	s_and_b64 vcc, exec, s[26:27]
	s_cbranch_vccz .LBB0_377
	s_barrier
.LBB0_377:
	s_ashr_i32 s15, s24, 1
	s_mov_b32 s86, 0x3a800000
	s_movk_i32 s67, 0x1000
	s_movk_i32 s87, 0x3fff
	s_cmp_eq_u32 s15, 2
	s_cbranch_scc1 .Latt_epi_tr
	s_cmp_eq_u32 s15, 5
	s_cbranch_scc1 .Latt_epi_tr
	s_branch .Latt_epi_rope
	s_cmp_lt_i32 s15, 5
	v_mbcnt_lo_u32_b32 v32, -1, 0
	v_mbcnt_hi_u32_b32 v32, -1, v32
	s_cbranch_scc1 .LBB0_380
	s_mov_b64 s[28:29], -1
	s_mov_b64 s[30:31], 0
	s_cmp_eq_u32 s15, 5
	s_mov_b64 s[26:27], 0
	s_cbranch_scc0 .LBB0_381
	s_mov_b64 s[28:29], 0
	s_mov_b64 s[26:27], -1
	s_branch .LBB0_381

; DI bf16_t f2bf(float a) { return (bf16_t)(pk_bf16(a, 0.f) & 0xffffu); }
; template <int EPI>
; DI void gemm_phase(const bf16_t* __restrict__ A, const bf16_t* __restrict__ Bt, const int K, const int N, const Params& p, const int layer_j, char* lds) {
;     ...
;                 const float sc = (region == 0 || region == 3) ? 0.125f * LOG2E : 1.0f;
;                 const float* cb = (const float*)(ws + OFF_ROPE) + (row0 & 2047) * 32 + fr;
;                 bf16_t* dst = PROJ + (size_t)row0 * ATT_IN + col0 + fr;
; #pragma unroll
;                 for (int ai = 0; ai < 2; ++ai)
; #pragma unroll
;                     for (int m = 0; m < 4; ++m)
; #pragma unroll
;                         for (int j = 0; j < 4; ++j)
; #pragma unroll
;                             for (int n = 0; n < 2; ++n) {
;                                 const int ro = ai * 128 + m * 16 + j;
;                                 const float c = cb[ro * 32 + n * 16], sn = cb[2048 * 32 + ro * 32 + n * 16];
;                                 const float x1 = acc[ai][0][m][n][j], x2 = acc[ai][1][m][n][j];
;                                 dst[(size_t)ro * ATT_IN + n * 16] = f2bf((x1 * c - x2 * sn) * sc); dst[(size_t)ro * ATT_IN + 32 + n * 16] = f2bf((x2 * c + x1 * sn) * sc);
;                                 if (n == 1 && (j & 1)) __builtin_amdgcn_sched_barrier(0); }
.Latt_epi_rope:
	v_mbcnt_lo_u32_b32 v204, -1, 0
	v_mbcnt_hi_u32_b32 v204, -1, v204
	s_mul_i32 s26, s71, 34
	s_add_i32 s26, s26, 0x20100
	v_and_b32_e32 v205, 15, v204
	v_lshrrev_b32_e32 v206, 4, v204
	v_mul_u32_u24_e32 v205, 136, v205
	v_lshl_add_u32 v205, v206, 3, v205
	v_add_u32_e32 v205, s26, v205
	v_lshrrev_b32_e32 v207, 3, v204
	v_and_b32_e32 v208, 7, v204
	v_mul_u32_u24_e32 v206, 136, v207
	v_lshl_add_u32 v206, v208, 4, v206
	v_add_u32_e32 v206, s26, v206
	v_readlane_b32 s26, v254, 7
	v_readlane_b32 s27, v254, 14
	v_lshlrev_b32_e32 v208, 4, v208
	v_add_u32_e32 v207, s26, v207
	s_lshl_b32 s27, s27, 1
	s_mov_b32 s26, 6144
	v_mad_u32_u24 v207, v207, s26, v208
	v_add_u32_e32 v207, s27, v207
	v_add_u32_e32 v208, 0xc000, v207
	v_readlane_b32 s26, v254, 7
	v_and_b32_e32 v211, 15, v204
	v_lshrrev_b32_e32 v212, 4, v204
	v_add_u32_e32 v211, s26, v211
	v_lshlrev_b32_e32 v211, 7, v211
	v_lshl_add_u32 v211, v212, 4, v211
	s_and_b32 s26, s22, 7
	s_lshl_b32 s26, s26, 15
	s_add_u32 s26, s10, s26
	s_addc_u32 s27, s11, 0
	s_add_u32 s28, s26, 0x40000
	s_addc_u32 s29, s27, 0
	s_mul_i32 s30, s22, 0x180000
	s_mul_hi_u32 s31, s22, 0x180000
	s_lshl_b32 s13, s24, 9
	s_add_u32 s30, s30, s13
	s_addc_u32 s31, s31, 0
	s_add_u32 s30, s30, s8
	s_addc_u32 s31, s31, s9
	s_cmp_lt_u32 s24, 2
	s_cselect_b32 s13, 0x3e38aa3b, 1.0
	s_cmp_eq_u32 s15, 3
	s_cselect_b32 s13, 0x3e38aa3b, s13
	global_load_dwordx4 v[154:157], v211, s[26:27]
	global_load_dwordx4 v[158:161], v211, s[26:27] offset:64
	global_load_dwordx4 v[162:165], v211, s[28:29]
	global_load_dwordx4 v[166:169], v211, s[28:29] offset:64
	v_add_u32_e32 v212, 0x800, v211
	global_load_dwordx4 v[170:173], v212, s[26:27]
	global_load_dwordx4 v[174:177], v212, s[26:27] offset:64
	global_load_dwordx4 v[178:181], v212, s[28:29]
	global_load_dwordx4 v[182:185], v212, s[28:29] offset:64
	s_waitcnt vmcnt(4)
	v_mul_f32_e32 v186, v74, v162
	v_mul_f32_e32 v187, v75, v163
	v_mul_f32_e32 v188, v76, v164
	v_mul_f32_e32 v189, v77, v165
	v_mul_f32_e32 v190, v74, v154
	v_mul_f32_e32 v136, v75, v155
	v_mul_f32_e32 v137, v76, v156
	v_mul_f32_e32 v213, v77, v157
	v_fma_f32 v74, v126, v162, v190
	v_fma_f32 v75, v127, v163, v136
	v_fma_f32 v76, v128, v164, v137
	v_fma_f32 v77, v129, v165, v213
	v_fma_f32 v126, v126, v154, -v186
	v_fma_f32 v127, v127, v155, -v187
	v_fma_f32 v128, v128, v156, -v188
	v_fma_f32 v129, v129, v157, -v189
	v_mul_f32_e32 v126, s13, v126
	v_mul_f32_e32 v127, s13, v127
	v_mul_f32_e32 v128, s13, v128
	v_mul_f32_e32 v129, s13, v129
	v_mul_f32_e32 v74, s13, v74
	v_mul_f32_e32 v75, s13, v75
	v_mul_f32_e32 v76, s13, v76
	v_mul_f32_e32 v77, s13, v77
	v_mul_f32_e32 v186, v34, v166
	v_mul_f32_e32 v187, v35, v167
	v_mul_f32_e32 v188, v36, v168
	v_mul_f32_e32 v189, v37, v169
	v_mul_f32_e32 v190, v34, v158
	v_mul_f32_e32 v136, v35, v159
	v_mul_f32_e32 v137, v36, v160
	v_mul_f32_e32 v213, v37, v161
	v_fma_f32 v34, v110, v166, v190
	v_fma_f32 v35, v111, v167, v136
	v_fma_f32 v36, v112, v168, v137
	v_fma_f32 v37, v113, v169, v213
	v_fma_f32 v110, v110, v158, -v186
	v_fma_f32 v111, v111, v159, -v187
	v_fma_f32 v112, v112, v160, -v188
	v_fma_f32 v113, v113, v161, -v189
	v_mul_f32_e32 v110, s13, v110
	v_mul_f32_e32 v111, s13, v111
	v_mul_f32_e32 v112, s13, v112
	v_mul_f32_e32 v113, s13, v113
	v_mul_f32_e32 v34, s13, v34
	v_mul_f32_e32 v35, s13, v35
	v_mul_f32_e32 v36, s13, v36
	v_mul_f32_e32 v37, s13, v37
	v_add_u32_e32 v212, 0x1000, v211
	global_load_dwordx4 v[154:157], v212, s[26:27]
	global_load_dwordx4 v[158:161], v212, s[26:27] offset:64
	global_load_dwordx4 v[162:165], v212, s[28:29]
	global_load_dwordx4 v[166:169], v212, s[28:29] offset:64
	s_waitcnt vmcnt(4)
	v_mul_f32_e32 v186, v62, v178
	v_mul_f32_e32 v187, v63, v179
	v_mul_f32_e32 v188, v64, v180
	v_mul_f32_e32 v189, v65, v181
	v_mul_f32_e32 v190, v62, v170
	v_mul_f32_e32 v136, v63, v171
	v_mul_f32_e32 v137, v64, v172
	v_mul_f32_e32 v213, v65, v173
	v_fma_f32 v62, v122, v178, v190
	v_fma_f32 v63, v123, v179, v136
	v_fma_f32 v64, v124, v180, v137
	v_fma_f32 v65, v125, v181, v213
	v_fma_f32 v122, v122, v170, -v186
	v_fma_f32 v123, v123, v171, -v187
	v_fma_f32 v124, v124, v172, -v188
	v_fma_f32 v125, v125, v173, -v189
	v_mul_f32_e32 v122, s13, v122
	v_mul_f32_e32 v123, s13, v123
	v_mul_f32_e32 v124, s13, v124
	v_mul_f32_e32 v125, s13, v125
	v_mul_f32_e32 v62, s13, v62
	v_mul_f32_e32 v63, s13, v63
	v_mul_f32_e32 v64, s13, v64
	v_mul_f32_e32 v65, s13, v65
	v_mul_f32_e32 v186, v24, v182
	v_mul_f32_e32 v187, v25, v183
	v_mul_f32_e32 v188, v26, v184
	v_mul_f32_e32 v189, v27, v185
	v_mul_f32_e32 v190, v24, v174
	v_mul_f32_e32 v136, v25, v175
	v_mul_f32_e32 v137, v26, v176
	v_mul_f32_e32 v213, v27, v177
	v_fma_f32 v24, v106, v182, v190
	v_fma_f32 v25, v107, v183, v136
	v_fma_f32 v26, v108, v184, v137
	v_fma_f32 v27, v109, v185, v213
	v_fma_f32 v106, v106, v174, -v186
	v_fma_f32 v107, v107, v175, -v187
	v_fma_f32 v108, v108, v176, -v188
	v_fma_f32 v109, v109, v177, -v189
	v_mul_f32_e32 v106, s13, v106
	v_mul_f32_e32 v107, s13, v107
	v_mul_f32_e32 v108, s13, v108
	v_mul_f32_e32 v109, s13, v109
	v_mul_f32_e32 v24, s13, v24
	v_mul_f32_e32 v25, s13, v25
	v_mul_f32_e32 v26, s13, v26
	v_mul_f32_e32 v27, s13, v27
	v_add_u32_e32 v212, 0x1800, v211
	global_load_dwordx4 v[170:173], v212, s[26:27]
	global_load_dwordx4 v[174:177], v212, s[26:27] offset:64
	global_load_dwordx4 v[178:181], v212, s[28:29]
	global_load_dwordx4 v[182:185], v212, s[28:29] offset:64
	s_waitcnt vmcnt(4)
; DI bf16_t f2bf(float a) { return (bf16_t)(pk_bf16(a, 0.f) & 0xffffu); }
; template <int EPI>
; DI void gemm_phase(const bf16_t* __restrict__ A, const bf16_t* __restrict__ Bt, const int K, const int N, const Params& p, const int layer_j, char* lds) {
;     ...
;                 const float sc = (region == 0 || region == 3) ? 0.125f * LOG2E : 1.0f;
;                 const float* cb = (const float*)(ws + OFF_ROPE) + (row0 & 2047) * 32 + fr;
;                 bf16_t* dst = PROJ + (size_t)row0 * ATT_IN + col0 + fr;
; #pragma unroll
;                 for (int ai = 0; ai < 2; ++ai)
; #pragma unroll
;                     for (int m = 0; m < 4; ++m)
; #pragma unroll
;                         for (int j = 0; j < 4; ++j)
; #pragma unroll
;                             for (int n = 0; n < 2; ++n) {
;                                 const int ro = ai * 128 + m * 16 + j;
;                                 const float c = cb[ro * 32 + n * 16], sn = cb[2048 * 32 + ro * 32 + n * 16];
;                                 const float x1 = acc[ai][0][m][n][j], x2 = acc[ai][1][m][n][j];
;                                 dst[(size_t)ro * ATT_IN + n * 16] = f2bf((x1 * c - x2 * sn) * sc); dst[(size_t)ro * ATT_IN + 32 + n * 16] = f2bf((x2 * c + x1 * sn) * sc);
;                                 if (n == 1 && (j & 1)) __builtin_amdgcn_sched_barrier(0); }
	v_mul_f32_e32 v186, v54, v162
	v_mul_f32_e32 v187, v55, v163
	v_mul_f32_e32 v188, v56, v164
	v_mul_f32_e32 v189, v57, v165
	v_mul_f32_e32 v190, v54, v154
	v_mul_f32_e32 v136, v55, v155
	v_mul_f32_e32 v137, v56, v156
	v_mul_f32_e32 v213, v57, v157
	v_fma_f32 v54, v118, v162, v190
	v_fma_f32 v55, v119, v163, v136
	v_fma_f32 v56, v120, v164, v137
	v_fma_f32 v57, v121, v165, v213
	v_fma_f32 v118, v118, v154, -v186
	v_fma_f32 v119, v119, v155, -v187
	v_fma_f32 v120, v120, v156, -v188
	v_fma_f32 v121, v121, v157, -v189
	v_mul_f32_e32 v118, s13, v118
	v_mul_f32_e32 v119, s13, v119
	v_mul_f32_e32 v120, s13, v120
	v_mul_f32_e32 v121, s13, v121
	v_mul_f32_e32 v54, s13, v54
	v_mul_f32_e32 v55, s13, v55
	v_mul_f32_e32 v56, s13, v56
	v_mul_f32_e32 v57, s13, v57
	v_mul_f32_e32 v186, v20, v166
	v_mul_f32_e32 v187, v21, v167
	v_mul_f32_e32 v188, v22, v168
	v_mul_f32_e32 v189, v23, v169
	v_mul_f32_e32 v190, v20, v158
	v_mul_f32_e32 v136, v21, v159
	v_mul_f32_e32 v137, v22, v160
	v_mul_f32_e32 v213, v23, v161
	v_fma_f32 v20, v102, v166, v190
	v_fma_f32 v21, v103, v167, v136
	v_fma_f32 v22, v104, v168, v137
	v_fma_f32 v23, v105, v169, v213
	v_fma_f32 v102, v102, v158, -v186
	v_fma_f32 v103, v103, v159, -v187
	v_fma_f32 v104, v104, v160, -v188
	v_fma_f32 v105, v105, v161, -v189
	v_mul_f32_e32 v102, s13, v102
	v_mul_f32_e32 v103, s13, v103
	v_mul_f32_e32 v104, s13, v104
	v_mul_f32_e32 v105, s13, v105
	v_mul_f32_e32 v20, s13, v20
	v_mul_f32_e32 v21, s13, v21
	v_mul_f32_e32 v22, s13, v22
	v_mul_f32_e32 v23, s13, v23
	v_add_u32_e32 v212, 0x4000, v211
	global_load_dwordx4 v[154:157], v212, s[26:27]
	global_load_dwordx4 v[158:161], v212, s[26:27] offset:64
	global_load_dwordx4 v[162:165], v212, s[28:29]
	global_load_dwordx4 v[166:169], v212, s[28:29] offset:64
	s_waitcnt vmcnt(4)
	v_mul_f32_e32 v186, v38, v178
	v_mul_f32_e32 v187, v39, v179
	v_mul_f32_e32 v188, v40, v180
	v_mul_f32_e32 v189, v41, v181
	v_mul_f32_e32 v190, v38, v170
	v_mul_f32_e32 v136, v39, v171
	v_mul_f32_e32 v137, v40, v172
	v_mul_f32_e32 v213, v41, v173
	v_fma_f32 v38, v114, v178, v190
	v_fma_f32 v39, v115, v179, v136
	v_fma_f32 v40, v116, v180, v137
	v_fma_f32 v41, v117, v181, v213
	v_fma_f32 v114, v114, v170, -v186
	v_fma_f32 v115, v115, v171, -v187
	v_fma_f32 v116, v116, v172, -v188
	v_fma_f32 v117, v117, v173, -v189
	v_mul_f32_e32 v114, s13, v114
	v_mul_f32_e32 v115, s13, v115
	v_mul_f32_e32 v116, s13, v116
	v_mul_f32_e32 v117, s13, v117
	v_mul_f32_e32 v38, s13, v38
	v_mul_f32_e32 v39, s13, v39
	v_mul_f32_e32 v40, s13, v40
	v_mul_f32_e32 v41, s13, v41
	v_mul_f32_e32 v186, v12, v182
	v_mul_f32_e32 v187, v13, v183
	v_mul_f32_e32 v188, v14, v184
	v_mul_f32_e32 v189, v15, v185
	v_mul_f32_e32 v190, v12, v174
	v_mul_f32_e32 v136, v13, v175
	v_mul_f32_e32 v137, v14, v176
	v_mul_f32_e32 v213, v15, v177
	v_fma_f32 v12, v94, v182, v190
	v_fma_f32 v13, v95, v183, v136
	v_fma_f32 v14, v96, v184, v137
	v_fma_f32 v15, v97, v185, v213
	v_fma_f32 v94, v94, v174, -v186
	v_fma_f32 v95, v95, v175, -v187
	v_fma_f32 v96, v96, v176, -v188
	v_fma_f32 v97, v97, v177, -v189
	v_mul_f32_e32 v94, s13, v94
	v_mul_f32_e32 v95, s13, v95
	v_mul_f32_e32 v96, s13, v96
	v_mul_f32_e32 v97, s13, v97
	v_mul_f32_e32 v12, s13, v12
	v_mul_f32_e32 v13, s13, v13
	v_mul_f32_e32 v14, s13, v14
	v_mul_f32_e32 v15, s13, v15
	v_add_u32_e32 v212, 0x4800, v211
	global_load_dwordx4 v[170:173], v212, s[26:27]
	global_load_dwordx4 v[174:177], v212, s[26:27] offset:64
	global_load_dwordx4 v[178:181], v212, s[28:29]
	global_load_dwordx4 v[182:185], v212, s[28:29] offset:64
	s_waitcnt vmcnt(4)
	v_mul_f32_e32 v186, v16, v162
	v_mul_f32_e32 v187, v17, v163
	v_mul_f32_e32 v188, v18, v164
	v_mul_f32_e32 v189, v19, v165
	v_mul_f32_e32 v190, v16, v154
	v_mul_f32_e32 v136, v17, v155
	v_mul_f32_e32 v137, v18, v156
	v_mul_f32_e32 v213, v19, v157
	v_fma_f32 v16, v98, v162, v190
	v_fma_f32 v17, v99, v163, v136
	v_fma_f32 v18, v100, v164, v137
	v_fma_f32 v19, v101, v165, v213
	v_fma_f32 v98, v98, v154, -v186
	v_fma_f32 v99, v99, v155, -v187
	v_fma_f32 v100, v100, v156, -v188
	v_fma_f32 v101, v101, v157, -v189
	v_mul_f32_e32 v98, s13, v98
	v_mul_f32_e32 v99, s13, v99
	v_mul_f32_e32 v100, s13, v100
	v_mul_f32_e32 v101, s13, v101
	v_mul_f32_e32 v16, s13, v16
	v_mul_f32_e32 v17, s13, v17
	v_mul_f32_e32 v18, s13, v18
	v_mul_f32_e32 v19, s13, v19
	v_mul_f32_e32 v186, v4, v166
	v_mul_f32_e32 v187, v5, v167
	v_mul_f32_e32 v188, v6, v168
	v_mul_f32_e32 v189, v7, v169
	v_mul_f32_e32 v190, v4, v158
	v_mul_f32_e32 v136, v5, v159
	v_mul_f32_e32 v137, v6, v160
	v_mul_f32_e32 v213, v7, v161
	v_fma_f32 v4, v66, v166, v190
	v_fma_f32 v5, v67, v167, v136
	v_fma_f32 v6, v68, v168, v137
	v_fma_f32 v7, v69, v169, v213
	v_fma_f32 v66, v66, v158, -v186
	v_fma_f32 v67, v67, v159, -v187
	v_fma_f32 v68, v68, v160, -v188
	v_fma_f32 v69, v69, v161, -v189
	v_mul_f32_e32 v66, s13, v66
	v_mul_f32_e32 v67, s13, v67
	v_mul_f32_e32 v68, s13, v68
	v_mul_f32_e32 v69, s13, v69
	v_mul_f32_e32 v4, s13, v4
	v_mul_f32_e32 v5, s13, v5
	v_mul_f32_e32 v6, s13, v6
	v_mul_f32_e32 v7, s13, v7
	v_add_u32_e32 v212, 0x5000, v211
	global_load_dwordx4 v[154:157], v212, s[26:27]
	global_load_dwordx4 v[158:161], v212, s[26:27] offset:64
	global_load_dwordx4 v[162:165], v212, s[28:29]
	global_load_dwordx4 v[166:169], v212, s[28:29] offset:64
	s_waitcnt vmcnt(4)
; DI bf16_t f2bf(float a) { return (bf16_t)(pk_bf16(a, 0.f) & 0xffffu); }
; template <int EPI>
; DI void gemm_phase(const bf16_t* __restrict__ A, const bf16_t* __restrict__ Bt, const int K, const int N, const Params& p, const int layer_j, char* lds) {
;     ...
;                 const float sc = (region == 0 || region == 3) ? 0.125f * LOG2E : 1.0f;
;                 const float* cb = (const float*)(ws + OFF_ROPE) + (row0 & 2047) * 32 + fr;
;                 bf16_t* dst = PROJ + (size_t)row0 * ATT_IN + col0 + fr;
; #pragma unroll
;                 for (int ai = 0; ai < 2; ++ai)
; #pragma unroll
;                     for (int m = 0; m < 4; ++m)
; #pragma unroll
;                         for (int j = 0; j < 4; ++j)
; #pragma unroll
;                             for (int n = 0; n < 2; ++n) {
;                                 const int ro = ai * 128 + m * 16 + j;
;                                 const float c = cb[ro * 32 + n * 16], sn = cb[2048 * 32 + ro * 32 + n * 16];
;                                 const float x1 = acc[ai][0][m][n][j], x2 = acc[ai][1][m][n][j];
;                                 dst[(size_t)ro * ATT_IN + n * 16] = f2bf((x1 * c - x2 * sn) * sc); dst[(size_t)ro * ATT_IN + 32 + n * 16] = f2bf((x2 * c + x1 * sn) * sc);
;                                 if (n == 1 && (j & 1)) __builtin_amdgcn_sched_barrier(0); }
	v_mul_f32_e32 v186, v8, v178
	v_mul_f32_e32 v187, v9, v179
	v_mul_f32_e32 v188, v10, v180
	v_mul_f32_e32 v189, v11, v181
	v_mul_f32_e32 v190, v8, v170
	v_mul_f32_e32 v136, v9, v171
	v_mul_f32_e32 v137, v10, v172
	v_mul_f32_e32 v213, v11, v173
	v_fma_f32 v8, v90, v178, v190
	v_fma_f32 v9, v91, v179, v136
	v_fma_f32 v10, v92, v180, v137
	v_fma_f32 v11, v93, v181, v213
	v_fma_f32 v90, v90, v170, -v186
	v_fma_f32 v91, v91, v171, -v187
	v_fma_f32 v92, v92, v172, -v188
	v_fma_f32 v93, v93, v173, -v189
	v_mul_f32_e32 v90, s13, v90
	v_mul_f32_e32 v91, s13, v91
	v_mul_f32_e32 v92, s13, v92
	v_mul_f32_e32 v93, s13, v93
	v_mul_f32_e32 v8, s13, v8
	v_mul_f32_e32 v9, s13, v9
	v_mul_f32_e32 v10, s13, v10
	v_mul_f32_e32 v11, s13, v11
	v_mul_f32_e32 v186, v0, v182
	v_mul_f32_e32 v187, v1, v183
	v_mul_f32_e32 v188, v2, v184
	v_mul_f32_e32 v189, v3, v185
	v_mul_f32_e32 v190, v0, v174
	v_mul_f32_e32 v136, v1, v175
	v_mul_f32_e32 v137, v2, v176
	v_mul_f32_e32 v213, v3, v177
	v_fma_f32 v0, v58, v182, v190
	v_fma_f32 v1, v59, v183, v136
	v_fma_f32 v2, v60, v184, v137
	v_fma_f32 v3, v61, v185, v213
	v_fma_f32 v58, v58, v174, -v186
	v_fma_f32 v59, v59, v175, -v187
	v_fma_f32 v60, v60, v176, -v188
	v_fma_f32 v61, v61, v177, -v189
	v_mul_f32_e32 v58, s13, v58
	v_mul_f32_e32 v59, s13, v59
	v_mul_f32_e32 v60, s13, v60
	v_mul_f32_e32 v61, s13, v61
	v_mul_f32_e32 v0, s13, v0
	v_mul_f32_e32 v1, s13, v1
	v_mul_f32_e32 v2, s13, v2
	v_mul_f32_e32 v3, s13, v3
	v_add_u32_e32 v212, 0x5800, v211
	global_load_dwordx4 v[170:173], v212, s[26:27]
	global_load_dwordx4 v[174:177], v212, s[26:27] offset:64
	global_load_dwordx4 v[178:181], v212, s[28:29]
	global_load_dwordx4 v[182:185], v212, s[28:29] offset:64
	s_waitcnt vmcnt(4)
	v_mul_f32_e32 v186, v78, v162
	v_mul_f32_e32 v187, v79, v163
	v_mul_f32_e32 v188, v80, v164
	v_mul_f32_e32 v189, v81, v165
	v_mul_f32_e32 v190, v78, v154
	v_mul_f32_e32 v136, v79, v155
	v_mul_f32_e32 v137, v80, v156
	v_mul_f32_e32 v213, v81, v157
	v_fma_f32 v78, v86, v162, v190
	v_fma_f32 v79, v87, v163, v136
	v_fma_f32 v80, v88, v164, v137
	v_fma_f32 v81, v89, v165, v213
	v_fma_f32 v86, v86, v154, -v186
	v_fma_f32 v87, v87, v155, -v187
	v_fma_f32 v88, v88, v156, -v188
	v_fma_f32 v89, v89, v157, -v189
	v_mul_f32_e32 v86, s13, v86
	v_mul_f32_e32 v87, s13, v87
	v_mul_f32_e32 v88, s13, v88
	v_mul_f32_e32 v89, s13, v89
	v_mul_f32_e32 v78, s13, v78
	v_mul_f32_e32 v79, s13, v79
	v_mul_f32_e32 v80, s13, v80
	v_mul_f32_e32 v81, s13, v81
	v_mul_f32_e32 v186, v46, v166
	v_mul_f32_e32 v187, v47, v167
	v_mul_f32_e32 v188, v48, v168
	v_mul_f32_e32 v189, v49, v169
	v_mul_f32_e32 v190, v46, v158
	v_mul_f32_e32 v136, v47, v159
	v_mul_f32_e32 v137, v48, v160
	v_mul_f32_e32 v213, v49, v161
	v_fma_f32 v46, v42, v166, v190
	v_fma_f32 v47, v43, v167, v136
	v_fma_f32 v48, v44, v168, v137
	v_fma_f32 v49, v45, v169, v213
	v_fma_f32 v42, v42, v158, -v186
	v_fma_f32 v43, v43, v159, -v187
	v_fma_f32 v44, v44, v160, -v188
	v_fma_f32 v45, v45, v161, -v189
	v_mul_f32_e32 v42, s13, v42
	v_mul_f32_e32 v43, s13, v43
	v_mul_f32_e32 v44, s13, v44
	v_mul_f32_e32 v45, s13, v45
	v_mul_f32_e32 v46, s13, v46
	v_mul_f32_e32 v47, s13, v47
	v_mul_f32_e32 v48, s13, v48
	v_mul_f32_e32 v49, s13, v49
	s_waitcnt vmcnt(0)
	v_mul_f32_e32 v186, v82, v178
	v_mul_f32_e32 v187, v83, v179
	v_mul_f32_e32 v188, v84, v180
	v_mul_f32_e32 v189, v85, v181
	v_mul_f32_e32 v190, v82, v170
	v_mul_f32_e32 v136, v83, v171
	v_mul_f32_e32 v137, v84, v172
	v_mul_f32_e32 v213, v85, v173
	v_fma_f32 v82, v70, v178, v190
	v_fma_f32 v83, v71, v179, v136
	v_fma_f32 v84, v72, v180, v137
	v_fma_f32 v85, v73, v181, v213
	v_fma_f32 v70, v70, v170, -v186
	v_fma_f32 v71, v71, v171, -v187
	v_fma_f32 v72, v72, v172, -v188
	v_fma_f32 v73, v73, v173, -v189
	v_mul_f32_e32 v70, s13, v70
	v_mul_f32_e32 v71, s13, v71
	v_mul_f32_e32 v72, s13, v72
	v_mul_f32_e32 v73, s13, v73
	v_mul_f32_e32 v82, s13, v82
	v_mul_f32_e32 v83, s13, v83
	v_mul_f32_e32 v84, s13, v84
	v_mul_f32_e32 v85, s13, v85
	v_mul_f32_e32 v186, v50, v182
	v_mul_f32_e32 v187, v51, v183
	v_mul_f32_e32 v188, v52, v184
	v_mul_f32_e32 v189, v53, v185
	v_mul_f32_e32 v190, v50, v174
	v_mul_f32_e32 v136, v51, v175
	v_mul_f32_e32 v137, v52, v176
	v_mul_f32_e32 v213, v53, v177
	v_fma_f32 v50, v28, v182, v190
	v_fma_f32 v51, v29, v183, v136
	v_fma_f32 v52, v30, v184, v137
	v_fma_f32 v53, v31, v185, v213
	v_fma_f32 v28, v28, v174, -v186
	v_fma_f32 v29, v29, v175, -v187
	v_fma_f32 v30, v30, v176, -v188
	v_fma_f32 v31, v31, v177, -v189
	v_mul_f32_e32 v28, s13, v28
	v_mul_f32_e32 v29, s13, v29
	v_mul_f32_e32 v30, s13, v30
	v_mul_f32_e32 v31, s13, v31
	v_mul_f32_e32 v50, s13, v50
	v_mul_f32_e32 v51, s13, v51
	v_mul_f32_e32 v52, s13, v52
	v_mul_f32_e32 v53, s13, v53
	v_cvt_pk_bf16_f32 v214, v126, v127
	v_cvt_pk_bf16_f32 v215, v128, v129
	v_cvt_pk_bf16_f32 v216, v110, v111
	v_cvt_pk_bf16_f32 v217, v112, v113
	v_cvt_pk_bf16_f32 v218, v74, v75
	v_cvt_pk_bf16_f32 v219, v76, v77
	v_cvt_pk_bf16_f32 v220, v34, v35
	v_cvt_pk_bf16_f32 v221, v36, v37
	ds_write_b64 v205, v[214:215]
	ds_write_b64 v205, v[216:217] offset:32
	ds_write_b64 v205, v[218:219] offset:64
	ds_write_b64 v205, v[220:221] offset:96
	ds_read2_b64 v[222:225], v206 offset1:1
	ds_read2_b64 v[226:229], v206 offset0:136 offset1:137
	s_waitcnt lgkmcnt(0)
	global_store_dwordx4 v207, v[222:225], s[30:31]
	global_store_dwordx4 v208, v[226:229], s[30:31]
	v_cvt_pk_bf16_f32 v214, v122, v123
	v_cvt_pk_bf16_f32 v215, v124, v125
	v_cvt_pk_bf16_f32 v216, v106, v107
	v_cvt_pk_bf16_f32 v217, v108, v109
	v_cvt_pk_bf16_f32 v218, v62, v63
	v_cvt_pk_bf16_f32 v219, v64, v65
	v_cvt_pk_bf16_f32 v220, v24, v25
	v_cvt_pk_bf16_f32 v221, v26, v27
	ds_write_b64 v205, v[214:215]
	ds_write_b64 v205, v[216:217] offset:32
	ds_write_b64 v205, v[218:219] offset:64
	ds_write_b64 v205, v[220:221] offset:96
	ds_read2_b64 v[222:225], v206 offset1:1
	ds_read2_b64 v[226:229], v206 offset0:136 offset1:137
	v_add_u32_e32 v209, 0x18000, v207
	v_add_u32_e32 v210, 0x18000, v208
	s_waitcnt lgkmcnt(0)
; DI bf16_t f2bf(float a) { return (bf16_t)(pk_bf16(a, 0.f) & 0xffffu); }
; template <int EPI>
; DI void gemm_phase(const bf16_t* __restrict__ A, const bf16_t* __restrict__ Bt, const int K, const int N, const Params& p, const int layer_j, char* lds) {
;     ...
;                 bf16_t* dst = PROJ + (size_t)row0 * ATT_IN + col0 + fr;
; #pragma unroll
;                 for (int ai = 0; ai < 2; ++ai)
; #pragma unroll
;                     for (int m = 0; m < 4; ++m)
; #pragma unroll
;                         for (int j = 0; j < 4; ++j)
; #pragma unroll
;                             for (int n = 0; n < 2; ++n) {
;                                 const int ro = ai * 128 + m * 16 + j;
;                                 const float c = cb[ro * 32 + n * 16], sn = cb[2048 * 32 + ro * 32 + n * 16];
;                                 const float x1 = acc[ai][0][m][n][j], x2 = acc[ai][1][m][n][j];
;                                 dst[(size_t)ro * ATT_IN + n * 16] = f2bf((x1 * c - x2 * sn) * sc); dst[(size_t)ro * ATT_IN + 32 + n * 16] = f2bf((x2 * c + x1 * sn) * sc);
;                                 if (n == 1 && (j & 1)) __builtin_amdgcn_sched_barrier(0); }
	global_store_dwordx4 v209, v[222:225], s[30:31]
	global_store_dwordx4 v210, v[226:229], s[30:31]
	v_cvt_pk_bf16_f32 v214, v118, v119
	v_cvt_pk_bf16_f32 v215, v120, v121
	v_cvt_pk_bf16_f32 v216, v102, v103
	v_cvt_pk_bf16_f32 v217, v104, v105
	v_cvt_pk_bf16_f32 v218, v54, v55
	v_cvt_pk_bf16_f32 v219, v56, v57
	v_cvt_pk_bf16_f32 v220, v20, v21
	v_cvt_pk_bf16_f32 v221, v22, v23
	ds_write_b64 v205, v[214:215]
	ds_write_b64 v205, v[216:217] offset:32
	ds_write_b64 v205, v[218:219] offset:64
	ds_write_b64 v205, v[220:221] offset:96
	ds_read2_b64 v[222:225], v206 offset1:1
	ds_read2_b64 v[226:229], v206 offset0:136 offset1:137
	v_add_u32_e32 v209, 0x30000, v207
	v_add_u32_e32 v210, 0x30000, v208
	s_waitcnt lgkmcnt(0)
	global_store_dwordx4 v209, v[222:225], s[30:31]
	global_store_dwordx4 v210, v[226:229], s[30:31]
	v_cvt_pk_bf16_f32 v214, v114, v115
	v_cvt_pk_bf16_f32 v215, v116, v117
	v_cvt_pk_bf16_f32 v216, v94, v95
	v_cvt_pk_bf16_f32 v217, v96, v97
	v_cvt_pk_bf16_f32 v218, v38, v39
	v_cvt_pk_bf16_f32 v219, v40, v41
	v_cvt_pk_bf16_f32 v220, v12, v13
	v_cvt_pk_bf16_f32 v221, v14, v15
	ds_write_b64 v205, v[214:215]
	ds_write_b64 v205, v[216:217] offset:32
	ds_write_b64 v205, v[218:219] offset:64
	ds_write_b64 v205, v[220:221] offset:96
	ds_read2_b64 v[222:225], v206 offset1:1
	ds_read2_b64 v[226:229], v206 offset0:136 offset1:137
	v_add_u32_e32 v209, 0x48000, v207
	v_add_u32_e32 v210, 0x48000, v208
	s_waitcnt lgkmcnt(0)
	global_store_dwordx4 v209, v[222:225], s[30:31]
	global_store_dwordx4 v210, v[226:229], s[30:31]
	v_cvt_pk_bf16_f32 v214, v98, v99
	v_cvt_pk_bf16_f32 v215, v100, v101
	v_cvt_pk_bf16_f32 v216, v66, v67
	v_cvt_pk_bf16_f32 v217, v68, v69
	v_cvt_pk_bf16_f32 v218, v16, v17
	v_cvt_pk_bf16_f32 v219, v18, v19
	v_cvt_pk_bf16_f32 v220, v4, v5
	v_cvt_pk_bf16_f32 v221, v6, v7
	ds_write_b64 v205, v[214:215]
	ds_write_b64 v205, v[216:217] offset:32
	ds_write_b64 v205, v[218:219] offset:64
	ds_write_b64 v205, v[220:221] offset:96
	ds_read2_b64 v[222:225], v206 offset1:1
	ds_read2_b64 v[226:229], v206 offset0:136 offset1:137
	v_add_u32_e32 v209, 0xc0000, v207
	v_add_u32_e32 v210, 0xc0000, v208
	s_waitcnt lgkmcnt(0)
	global_store_dwordx4 v209, v[222:225], s[30:31]
	global_store_dwordx4 v210, v[226:229], s[30:31]
	v_cvt_pk_bf16_f32 v214, v90, v91
	v_cvt_pk_bf16_f32 v215, v92, v93
	v_cvt_pk_bf16_f32 v216, v58, v59
	v_cvt_pk_bf16_f32 v217, v60, v61
	v_cvt_pk_bf16_f32 v218, v8, v9
	v_cvt_pk_bf16_f32 v219, v10, v11
	v_cvt_pk_bf16_f32 v220, v0, v1
	v_cvt_pk_bf16_f32 v221, v2, v3
	ds_write_b64 v205, v[214:215]
	ds_write_b64 v205, v[216:217] offset:32
	ds_write_b64 v205, v[218:219] offset:64
	ds_write_b64 v205, v[220:221] offset:96
	ds_read2_b64 v[222:225], v206 offset1:1
	ds_read2_b64 v[226:229], v206 offset0:136 offset1:137
	v_add_u32_e32 v209, 0xd8000, v207
	v_add_u32_e32 v210, 0xd8000, v208
	s_waitcnt lgkmcnt(0)
	global_store_dwordx4 v209, v[222:225], s[30:31]
	global_store_dwordx4 v210, v[226:229], s[30:31]
	v_cvt_pk_bf16_f32 v214, v86, v87
	v_cvt_pk_bf16_f32 v215, v88, v89
	v_cvt_pk_bf16_f32 v216, v42, v43
	v_cvt_pk_bf16_f32 v217, v44, v45
	v_cvt_pk_bf16_f32 v218, v78, v79
	v_cvt_pk_bf16_f32 v219, v80, v81
	v_cvt_pk_bf16_f32 v220, v46, v47
	v_cvt_pk_bf16_f32 v221, v48, v49
	ds_write_b64 v205, v[214:215]
	ds_write_b64 v205, v[216:217] offset:32
	ds_write_b64 v205, v[218:219] offset:64
	ds_write_b64 v205, v[220:221] offset:96
	ds_read2_b64 v[222:225], v206 offset1:1
	ds_read2_b64 v[226:229], v206 offset0:136 offset1:137
	v_add_u32_e32 v209, 0xf0000, v207
	v_add_u32_e32 v210, 0xf0000, v208
	s_waitcnt lgkmcnt(0)
	global_store_dwordx4 v209, v[222:225], s[30:31]
	global_store_dwordx4 v210, v[226:229], s[30:31]
	v_cvt_pk_bf16_f32 v214, v70, v71
	v_cvt_pk_bf16_f32 v215, v72, v73
	v_cvt_pk_bf16_f32 v216, v28, v29
	v_cvt_pk_bf16_f32 v217, v30, v31
	v_cvt_pk_bf16_f32 v218, v82, v83
	v_cvt_pk_bf16_f32 v219, v84, v85
	v_cvt_pk_bf16_f32 v220, v50, v51
	v_cvt_pk_bf16_f32 v221, v52, v53
	ds_write_b64 v205, v[214:215]
	ds_write_b64 v205, v[216:217] offset:32
	ds_write_b64 v205, v[218:219] offset:64
	ds_write_b64 v205, v[220:221] offset:96
	ds_read2_b64 v[222:225], v206 offset1:1
	ds_read2_b64 v[226:229], v206 offset0:136 offset1:137
	v_add_u32_e32 v209, 0x108000, v207
	v_add_u32_e32 v210, 0x108000, v208
	s_waitcnt lgkmcnt(0)
	global_store_dwordx4 v209, v[222:225], s[30:31]
	global_store_dwordx4 v210, v[226:229], s[30:31]
	s_branch .LBB0_385
; DI unsigned pk_bf16(float a, float b) { f32x2_t v = {a, b}; bf16x2_t r = __builtin_convertvector(v, bf16x2_t); return __builtin_bit_cast(unsigned, r); }
; template <int EPI>
; DI void gemm_phase(const bf16_t* __restrict__ A, const bf16_t* __restrict__ Bt, const int K, const int N, const Params& p, const int layer_j, char* lds) {
;     ...
;             if (region == 2 || region == 5) {
;                 const int vc0 = (region == 2 ? col0 - 1024 : 512 + col0 - 2560);
;                 const int b = row0 >> 11, t0 = row0 & 2047;
;                 bf16_t* dst = VT + ((size_t)(b * 1024 + vc0 + fr)) * SEQ + t0;
; #pragma unroll
;                 for (int bj = 0; bj < 2; ++bj)
; #pragma unroll
;                     for (int n = 0; n < 2; ++n)
; #pragma unroll
;                         for (int ai = 0; ai < 2; ++ai)
; #pragma unroll
;                             for (int m = 0; m < 4; ++m) { u32x2 o; o[0] = pk_bf16(acc[ai][bj][m][n][0], acc[ai][bj][m][n][1]); o[1] = pk_bf16(acc[ai][bj][m][n][2], acc[ai][bj][m][n][3]);
;                                 *(u32x2*)(dst + (size_t)(bj * 32 + n * 16) * SEQ + ai * 128 + m * 16) = o; }
.Latt_epi_tr:
	v_mbcnt_lo_u32_b32 v204, -1, 0
	v_mbcnt_hi_u32_b32 v204, -1, v204
	s_mul_i32 s26, s71, 34
	s_add_i32 s26, s26, 0x20100
	v_and_b32_e32 v205, 15, v204
	v_lshrrev_b32_e32 v206, 4, v204
	v_mul_u32_u24_e32 v205, 136, v205
	v_lshl_add_u32 v205, v206, 3, v205
	v_add_u32_e32 v205, s26, v205
	v_lshrrev_b32_e32 v207, 3, v204
	v_and_b32_e32 v208, 7, v204
	v_mul_u32_u24_e32 v206, 136, v207
	v_lshl_add_u32 v206, v208, 4, v206
	v_add_u32_e32 v206, s26, v206
	v_readlane_b32 s26, v254, 14
	v_readlane_b32 s27, v254, 7
	v_lshlrev_b32_e32 v208, 4, v208
	v_add_u32_e32 v207, s26, v207
	s_lshl_b32 s27, s27, 1
	s_mov_b32 s26, 4096
	v_mad_u32_u24 v207, v207, s26, v208
	v_add_u32_e32 v207, s27, v207
	v_add_u32_e32 v208, 0x8000, v207
	s_lshr_b32 s26, s22, 3
	s_lshl_b32 s26, s26, 10
	s_lshl_b32 s27, s24, 8
	s_add_i32 s26, s26, s27
	s_movk_i32 s27, 0x800
	s_cmp_eq_u32 s15, 2
	s_cselect_b32 s27, 0x400, s27
	s_sub_u32 s26, s26, s27
	s_lshl_b32 s26, s26, 12
	s_and_b32 s27, s22, 7
	s_lshl_b32 s27, s27, 9
	s_add_u32 s26, s26, s27
	s_add_u32 s30, s26, s6
	s_addc_u32 s31, s7, 0
	v_cvt_pk_bf16_f32 v214, v126, v127
	v_cvt_pk_bf16_f32 v215, v128, v129
	v_cvt_pk_bf16_f32 v216, v122, v123
	v_cvt_pk_bf16_f32 v217, v124, v125
	v_cvt_pk_bf16_f32 v218, v118, v119
	v_cvt_pk_bf16_f32 v219, v120, v121
	v_cvt_pk_bf16_f32 v220, v114, v115
	v_cvt_pk_bf16_f32 v221, v116, v117
	ds_write_b64 v205, v[214:215]
	ds_write_b64 v205, v[216:217] offset:32
	ds_write_b64 v205, v[218:219] offset:64
	ds_write_b64 v205, v[220:221] offset:96
	ds_read2_b64 v[222:225], v206 offset1:1
	ds_read2_b64 v[226:229], v206 offset0:136 offset1:137
	s_waitcnt lgkmcnt(0)
	global_store_dwordx4 v207, v[222:225], s[30:31]
	global_store_dwordx4 v208, v[226:229], s[30:31]
	v_cvt_pk_bf16_f32 v214, v98, v99
	v_cvt_pk_bf16_f32 v215, v100, v101
	v_cvt_pk_bf16_f32 v216, v90, v91
	v_cvt_pk_bf16_f32 v217, v92, v93
	v_cvt_pk_bf16_f32 v218, v86, v87
	v_cvt_pk_bf16_f32 v219, v88, v89
	v_cvt_pk_bf16_f32 v220, v70, v71
	v_cvt_pk_bf16_f32 v221, v72, v73
	ds_write_b64 v205, v[214:215]
	ds_write_b64 v205, v[216:217] offset:32
	ds_write_b64 v205, v[218:219] offset:64
	ds_write_b64 v205, v[220:221] offset:96
	ds_read2_b64 v[222:225], v206 offset1:1
	ds_read2_b64 v[226:229], v206 offset0:136 offset1:137
	v_add_u32_e32 v209, 0x100, v207
	v_add_u32_e32 v210, 0x100, v208
	s_waitcnt lgkmcnt(0)
	global_store_dwordx4 v209, v[222:225], s[30:31]
	global_store_dwordx4 v210, v[226:229], s[30:31]
	v_cvt_pk_bf16_f32 v214, v110, v111
	v_cvt_pk_bf16_f32 v215, v112, v113
	v_cvt_pk_bf16_f32 v216, v106, v107
	v_cvt_pk_bf16_f32 v217, v108, v109
	v_cvt_pk_bf16_f32 v218, v102, v103
	v_cvt_pk_bf16_f32 v219, v104, v105
	v_cvt_pk_bf16_f32 v220, v94, v95
	v_cvt_pk_bf16_f32 v221, v96, v97
	ds_write_b64 v205, v[214:215]
	ds_write_b64 v205, v[216:217] offset:32
	ds_write_b64 v205, v[218:219] offset:64
	ds_write_b64 v205, v[220:221] offset:96
	ds_read2_b64 v[222:225], v206 offset1:1
	ds_read2_b64 v[226:229], v206 offset0:136 offset1:137
	v_add_u32_e32 v209, 0x10000, v207
	v_add_u32_e32 v210, 0x10000, v208
	s_waitcnt lgkmcnt(0)
	global_store_dwordx4 v209, v[222:225], s[30:31]
	global_store_dwordx4 v210, v[226:229], s[30:31]
	v_cvt_pk_bf16_f32 v214, v66, v67
	v_cvt_pk_bf16_f32 v215, v68, v69
	v_cvt_pk_bf16_f32 v216, v58, v59
	v_cvt_pk_bf16_f32 v217, v60, v61
	v_cvt_pk_bf16_f32 v218, v42, v43
	v_cvt_pk_bf16_f32 v219, v44, v45
	v_cvt_pk_bf16_f32 v220, v28, v29
	v_cvt_pk_bf16_f32 v221, v30, v31
	ds_write_b64 v205, v[214:215]
	ds_write_b64 v205, v[216:217] offset:32
	ds_write_b64 v205, v[218:219] offset:64
	ds_write_b64 v205, v[220:221] offset:96
	ds_read2_b64 v[222:225], v206 offset1:1
	ds_read2_b64 v[226:229], v206 offset0:136 offset1:137
	v_add_u32_e32 v209, 0x10100, v207
	v_add_u32_e32 v210, 0x10100, v208
	s_waitcnt lgkmcnt(0)
	global_store_dwordx4 v209, v[222:225], s[30:31]
	global_store_dwordx4 v210, v[226:229], s[30:31]
	v_cvt_pk_bf16_f32 v214, v74, v75
	v_cvt_pk_bf16_f32 v215, v76, v77
	v_cvt_pk_bf16_f32 v216, v62, v63
	v_cvt_pk_bf16_f32 v217, v64, v65
	v_cvt_pk_bf16_f32 v218, v54, v55
	v_cvt_pk_bf16_f32 v219, v56, v57
	v_cvt_pk_bf16_f32 v220, v38, v39
	v_cvt_pk_bf16_f32 v221, v40, v41
	ds_write_b64 v205, v[214:215]
	ds_write_b64 v205, v[216:217] offset:32
	ds_write_b64 v205, v[218:219] offset:64
	ds_write_b64 v205, v[220:221] offset:96
	ds_read2_b64 v[222:225], v206 offset1:1
	ds_read2_b64 v[226:229], v206 offset0:136 offset1:137
	v_add_u32_e32 v209, 0x20000, v207
	v_add_u32_e32 v210, 0x20000, v208
	s_waitcnt lgkmcnt(0)
	global_store_dwordx4 v209, v[222:225], s[30:31]
	global_store_dwordx4 v210, v[226:229], s[30:31]
	v_cvt_pk_bf16_f32 v214, v16, v17
	v_cvt_pk_bf16_f32 v215, v18, v19
	v_cvt_pk_bf16_f32 v216, v8, v9
	v_cvt_pk_bf16_f32 v217, v10, v11
	v_cvt_pk_bf16_f32 v218, v78, v79
	v_cvt_pk_bf16_f32 v219, v80, v81
	v_cvt_pk_bf16_f32 v220, v82, v83
	v_cvt_pk_bf16_f32 v221, v84, v85
	ds_write_b64 v205, v[214:215]
	ds_write_b64 v205, v[216:217] offset:32
	ds_write_b64 v205, v[218:219] offset:64
	ds_write_b64 v205, v[220:221] offset:96
	ds_read2_b64 v[222:225], v206 offset1:1
	ds_read2_b64 v[226:229], v206 offset0:136 offset1:137
	v_add_u32_e32 v209, 0x20100, v207
	v_add_u32_e32 v210, 0x20100, v208
	s_waitcnt lgkmcnt(0)
	global_store_dwordx4 v209, v[222:225], s[30:31]
	global_store_dwordx4 v210, v[226:229], s[30:31]
	v_cvt_pk_bf16_f32 v214, v34, v35
	v_cvt_pk_bf16_f32 v215, v36, v37
	v_cvt_pk_bf16_f32 v216, v24, v25
	v_cvt_pk_bf16_f32 v217, v26, v27
	v_cvt_pk_bf16_f32 v218, v20, v21
	v_cvt_pk_bf16_f32 v219, v22, v23
	v_cvt_pk_bf16_f32 v220, v12, v13
	v_cvt_pk_bf16_f32 v221, v14, v15
	ds_write_b64 v205, v[214:215]
	ds_write_b64 v205, v[216:217] offset:32
	ds_write_b64 v205, v[218:219] offset:64
	ds_write_b64 v205, v[220:221] offset:96
	ds_read2_b64 v[222:225], v206 offset1:1
	ds_read2_b64 v[226:229], v206 offset0:136 offset1:137
	v_add_u32_e32 v209, 0x30000, v207
	v_add_u32_e32 v210, 0x30000, v208
	s_waitcnt lgkmcnt(0)
	global_store_dwordx4 v209, v[222:225], s[30:31]
	global_store_dwordx4 v210, v[226:229], s[30:31]
	v_cvt_pk_bf16_f32 v214, v4, v5
	v_cvt_pk_bf16_f32 v215, v6, v7
	v_cvt_pk_bf16_f32 v216, v0, v1
	v_cvt_pk_bf16_f32 v217, v2, v3
	v_cvt_pk_bf16_f32 v218, v46, v47
	v_cvt_pk_bf16_f32 v219, v48, v49
	v_cvt_pk_bf16_f32 v220, v50, v51
	v_cvt_pk_bf16_f32 v221, v52, v53
	ds_write_b64 v205, v[214:215]
	ds_write_b64 v205, v[216:217] offset:32
	ds_write_b64 v205, v[218:219] offset:64
	ds_write_b64 v205, v[220:221] offset:96
	ds_read2_b64 v[222:225], v206 offset1:1
	ds_read2_b64 v[226:229], v206 offset0:136 offset1:137
	v_add_u32_e32 v209, 0x30100, v207
	v_add_u32_e32 v210, 0x30100, v208
	s_waitcnt lgkmcnt(0)
	global_store_dwordx4 v209, v[222:225], s[30:31]
	global_store_dwordx4 v210, v[226:229], s[30:31]
	s_branch .LBB0_385
